# EpiResid epilogues (down/out GEMMs): per-pass parameter loads issued together, one wait instead of three
# speedup vs baseline: 1.0009x; 1.0009x over previous
; #define RES_LOADG(slot, g_) do { const int ro_ = ((g_) >> 2) * HALF + ((g_) & 3) * 16; \
;                 _Pragma("unroll") for (int n = 0; n < 2; ++n) xa[slot][n] = *(const f32x4*)(sl + rbase + (size_t)ro_ * 2048 + bj * HALF + 4 * n); \
;                 ms[slot] = *(const f2_t_*)(stp + 2 * (row0 + ro_)); } while (0)
;     __device__ __forceinline__ void operator()(const f32x4 (&acc)[2][2][4][2], const Unit& u, int wr, int wc, int fr, int fq) const {
;     ...
; #pragma unroll
;         for (int bj = 0; bj < 2; ++bj) {
;             f32x4 mv[2], ag[2], ab[2];
; #pragma unroll
;             for (int n = 0; n < 2; ++n) { mv[n] = *(const f32x4*)(mp + col0 + bj * HALF + 4 * n) * coef;
;                 const f32x4 g4 = *(const f32x4*)(lg + col0 + bj * HALF + 4 * n), b4 = *(const f32x4*)(lb + col0 + bj * HALF + 4 * n);
;                 const f32x4 g4s = ln ? g4 : (f32x4){1.f, 1.f, 1.f, 1.f}, b4s = ln ? b4 : (f32x4){0.f, 0.f, 0.f, 0.f};
;                 ag[n] = g4s * al; ab[n] = b4s * al; }
;             f32x4 xa[3][2]; f2_t_ ms[3];
;     ...
;             RES_LOADG(0, 0); RES_LOADG(1, 1);
.LBB0_325:
	s_ashr_i32 s4, s74, 3
	s_mul_hi_i32 s5, s4, 0x12000
	s_mul_i32 s4, s4, 0x12000
	v_lshl_or_b32 v148, s75, 8, v220
	s_add_u32 s4, s59, s4
	v_ashrrev_i32_e32 v149, 31, v148
	s_addc_u32 s5, s60, s5
	v_lshlrev_b64 v[138:139], 2, v[148:149]
	v_lshl_add_u64 v[136:137], s[4:5], 0, v[138:139]
	v_add_co_u32_e32 v132, vcc, 0x4000, v136
	v_lshl_add_u64 v[166:167], s[6:7], 0, v[138:139]
	s_nop 0
	v_addc_co_u32_e32 v133, vcc, 0, v137, vcc
	global_load_dwordx4 v[132:135], v[132:133], off
	s_nop 0
	global_load_dwordx4 v[140:143], v[166:167], off
	v_lshl_add_u64 v[168:169], s[22:23], 0, v[138:139]
	v_cndmask_b32_e64 v138, 0, 1, s[30:31]
	v_mov_b32_e32 v174, 0x3fb504f3
	v_cmp_ne_u32_e64 s[4:5], 1, v138
	s_andn2_b64 vcc, exec, s[30:31]
	v_mov_b32_e32 v182, 0x3fb504f3
	v_mov_b32_e32 v183, 0x3fb504f3
	v_mov_b32_e32 v180, 0x3fb504f3
	v_mov_b32_e32 v181, 0x3fb504f3
	s_mov_b64 s[40:41], 0x4000
	v_lshl_add_u64 v[172:173], v[136:137], 0, s[40:41]
	global_load_dwordx4 v[144:147], v[172:173], off offset:16
	global_load_dwordx4 v[136:139], v[166:167], off offset:16
	s_mov_b32 s40, 0x3fb504f3
	v_mov_b32_e32 v175, 0x3fb504f3
	v_mov_b32_e32 v184, 0x3fb504f3
	v_mov_b32_e32 v185, 0x3fb504f3
	s_cbranch_vccnz .LBB0_329
	global_load_dwordx4 v[244:247], v[168:169], off
	global_load_dwordx4 v[162:165], v[168:169], off offset:16
	s_waitcnt vmcnt(0)
	v_pk_mul_f32 v[180:181], v[246:247], s[40:41] op_sel_hi:[1,0]
	v_pk_mul_f32 v[182:183], v[244:245], s[40:41] op_sel_hi:[1,0]
	v_pk_mul_f32 v[184:185], v[164:165], s[40:41] op_sel_hi:[1,0]
	v_pk_mul_f32 v[174:175], v[162:163], s[40:41] op_sel_hi:[1,0]
.LBB0_327:
.LBB0_329:
	s_waitcnt vmcnt(0)
	v_pk_mul_f32 v[140:141], v[140:141], s[40:41] op_sel_hi:[1,0]
	v_pk_mul_f32 v[142:143], v[142:143], s[40:41] op_sel_hi:[1,0]
	v_cndmask_b32_e64 v190, v140, 0, s[28:29]
	v_lshl_add_u32 v140, s74, 8, v218
	v_cndmask_b32_e64 v191, v141, 0, s[28:29]
	v_ashrrev_i32_e32 v141, 31, v140
	v_cndmask_b32_e64 v205, v143, 0, s[28:29]
	v_cndmask_b32_e64 v204, v142, 0, s[28:29]
	v_lshlrev_b64 v[142:143], 11, v[140:141]
	v_lshl_add_u64 v[142:143], v[142:143], 0, v[148:149]
	v_lshlrev_b64 v[170:171], 2, v[142:143]
	v_pk_mul_f32 v[212:213], v[134:135], 0.5 op_sel_hi:[1,0]
	v_pk_mul_f32 v[210:211], v[132:133], 0.5 op_sel_hi:[1,0]
	v_pk_mul_f32 v[132:133], v[138:139], s[40:41] op_sel_hi:[1,0]
	v_pk_mul_f32 v[134:135], v[136:137], s[40:41] op_sel_hi:[1,0]
	v_lshl_add_u64 v[164:165], s[20:21], 0, v[170:171]
	s_mov_b64 s[40:41], 0x20000
	v_cndmask_b32_e64 v209, v133, 0, s[28:29]
	v_cndmask_b32_e64 v208, v132, 0, s[28:29]
	v_lshl_add_u64 v[132:133], v[164:165], 0, s[40:41]
	s_mov_b32 s40, 0x20000
	v_lshlrev_b32_e32 v140, 1, v140
	v_add_co_u32_e32 v176, vcc, s40, v164
	v_ashrrev_i32_e32 v141, 31, v140
	s_nop 0
	v_addc_co_u32_e32 v177, vcc, 0, v165, vcc
	v_pk_mul_f32 v[188:189], v[146:147], 0.5 op_sel_hi:[1,0]
	v_pk_mul_f32 v[186:187], v[144:145], 0.5 op_sel_hi:[1,0]
	v_lshl_add_u64 v[162:163], v[140:141], 2, s[34:35]
	global_load_dwordx4 v[148:151], v[164:165], off offset:16
	global_load_dwordx4 v[238:241], v[164:165], off
	global_load_dwordx4 v[144:147], v[176:177], off
	global_load_dwordx4 v[136:139], v[132:133], off offset:16
	global_load_dwordx2 v[222:223], v[162:163], off
	global_load_dwordx2 v[216:217], v[162:163], off offset:128
	s_mov_b64 s[42:43], 0x40000
	v_lshl_add_u64 v[132:133], v[164:165], 0, s[42:43]
	s_mov_b32 s42, 0x40000
	v_add_co_u32_e32 v178, vcc, s42, v164
	v_pk_fma_f32 v[130:131], v[130:131], v[212:213], v[204:205]
	s_nop 0
	v_addc_co_u32_e32 v179, vcc, 0, v165, vcc
	v_pk_fma_f32 v[128:129], v[128:129], v[210:211], v[190:191]
	v_cndmask_b32_e64 v207, v135, 0, s[28:29]
	v_cndmask_b32_e64 v206, v134, 0, s[28:29]
	global_load_dwordx4 v[140:143], v[178:179], off
	s_nop 0
	global_load_dwordx4 v[132:135], v[132:133], off offset:16
	s_nop 0
	global_load_dwordx2 v[214:215], v[162:163], off offset:256
	v_lshl_add_u64 v[170:171], s[8:9], 0, v[170:171]
	v_pk_fma_f32 v[126:127], v[126:127], v[188:189], v[208:209]
	v_pk_fma_f32 v[124:125], v[124:125], v[186:187], v[206:207]
	s_mov_b32 s43, 0x60000
	s_mov_b64 s[74:75], 0x60000
	v_pk_fma_f32 v[120:121], v[120:121], v[210:211], v[190:191]
	v_pk_fma_f32 v[122:123], v[122:123], v[212:213], v[204:205]
	v_pk_fma_f32 v[118:119], v[118:119], v[188:189], v[208:209]
	v_pk_fma_f32 v[116:117], v[116:117], v[186:187], v[206:207]
	v_pk_fma_f32 v[112:113], v[112:113], v[210:211], v[190:191]
	v_pk_fma_f32 v[114:115], v[114:115], v[212:213], v[204:205]
	v_pk_fma_f32 v[108:109], v[108:109], v[186:187], v[206:207]
	v_pk_fma_f32 v[110:111], v[110:111], v[188:189], v[208:209]
	v_pk_fma_f32 v[104:105], v[104:105], v[210:211], v[190:191]
	v_pk_fma_f32 v[106:107], v[106:107], v[212:213], v[204:205]
	v_pk_fma_f32 v[102:103], v[102:103], v[188:189], v[208:209]
	v_pk_fma_f32 v[100:101], v[100:101], v[186:187], v[206:207]
	v_pk_fma_f32 v[98:99], v[98:99], v[212:213], v[204:205]
	v_pk_fma_f32 v[96:97], v[96:97], v[210:211], v[190:191]
	v_pk_fma_f32 v[94:95], v[94:95], v[188:189], v[208:209]
	v_pk_fma_f32 v[92:93], v[92:93], v[186:187], v[206:207]
	v_pk_fma_f32 v[90:91], v[90:91], v[212:213], v[204:205]
	v_pk_fma_f32 v[88:89], v[88:89], v[210:211], v[190:191]
	v_pk_fma_f32 v[86:87], v[86:87], v[188:189], v[208:209]
	v_pk_fma_f32 v[84:85], v[84:85], v[186:187], v[206:207]
	v_pk_fma_f32 v[80:81], v[80:81], v[210:211], v[190:191]
	v_pk_fma_f32 v[82:83], v[82:83], v[212:213], v[204:205]
	v_pk_fma_f32 v[78:79], v[78:79], v[188:189], v[208:209]
	v_pk_fma_f32 v[76:77], v[76:77], v[186:187], v[206:207]
	v_pk_fma_f32 v[74:75], v[74:75], v[212:213], v[204:205]
	v_pk_fma_f32 v[72:73], v[72:73], v[210:211], v[190:191]
	v_pk_fma_f32 v[70:71], v[70:71], v[188:189], v[208:209]
	v_pk_fma_f32 v[68:69], v[68:69], v[186:187], v[206:207]
	s_waitcnt vmcnt(0)
; #define RES_LOADG(slot, g_) do { const int ro_ = ((g_) >> 2) * HALF + ((g_) & 3) * 16; \
;                 _Pragma("unroll") for (int n = 0; n < 2; ++n) xa[slot][n] = *(const f32x4*)(sl + rbase + (size_t)ro_ * 2048 + bj * HALF + 4 * n); \
;                 ms[slot] = *(const f2_t_*)(stp + 2 * (row0 + ro_)); } while (0)
;     __device__ __forceinline__ void operator()(const f32x4 (&acc)[2][2][4][2], const Unit& u, int wr, int wc, int fr, int fq) const {
;     ...
; #pragma unroll
;             for (int gi = 0; gi < 8; ++gi) {
;                 const int ai = gi >> 2, m = gi & 3;
;                 if (gi + 2 < 8) RES_LOADG((gi + 2) % 3, gi + 2);
;                 asm volatile("" ::: "memory");
;                 float* rowp = xl + rbase + (size_t)(ai * HALF + m * 16) * 2048 + bj * HALF;
;                 const float mean = ln ? ms[gi % 3][0] : 0.f, rstd = ln ? ms[gi % 3][1] : 1.f;
; #pragma unroll
;                 for (int n = 0; n < 2; ++n) { const f32x4 t = ag[n] * rstd;
;                     *(f32x4*)(rowp + 4 * n) = (xa[gi % 3][n] - mean) * t + (ab[n] + mv[n] * acc[ai][bj][m][n]); }
;                 asm volatile("" ::: "memory");
;             }
	v_cndmask_b32_e64 v192, v222, 0, s[28:29]
	v_cndmask_b32_e64 v222, v223, 1.0, s[28:29]
	v_pk_mul_f32 v[230:231], v[182:183], v[222:223] op_sel_hi:[1,0]
	v_pk_mul_f32 v[232:233], v[180:181], v[222:223] op_sel_hi:[1,0]
	v_sub_f32_e32 v239, v239, v192
	v_sub_f32_e32 v238, v238, v192
	v_sub_f32_e32 v241, v241, v192
	v_sub_f32_e32 v240, v240, v192
	v_pk_fma_f32 v[130:131], v[232:233], v[240:241], v[130:131]
	v_pk_fma_f32 v[128:129], v[230:231], v[238:239], v[128:129]
	global_store_dwordx4 v[170:171], v[128:131], off
	v_sub_f32_e32 v149, v149, v192
	v_sub_f32_e32 v148, v148, v192
	v_pk_mul_f32 v[128:129], v[174:175], v[222:223] op_sel_hi:[1,0]
	v_pk_mul_f32 v[130:131], v[184:185], v[222:223] op_sel_hi:[1,0]
	v_sub_f32_e32 v151, v151, v192
	v_sub_f32_e32 v150, v150, v192
	v_pk_fma_f32 v[126:127], v[130:131], v[150:151], v[126:127]
	v_pk_fma_f32 v[124:125], v[128:129], v[148:149], v[124:125]
	global_store_dwordx4 v[170:171], v[124:127], off offset:16
	v_add_co_u32_e32 v148, vcc, s43, v164
	s_nop 0
	v_lshl_add_u64 v[124:125], v[164:165], 0, s[74:75]
	v_addc_co_u32_e32 v149, vcc, 0, v165, vcc
	global_load_dwordx4 v[128:131], v[148:149], off
	s_nop 0
	global_load_dwordx4 v[124:127], v[124:125], off offset:16
	s_nop 0
	global_load_dwordx2 v[150:151], v[162:163], off offset:384
	v_cndmask_b32_e64 v192, v216, 0, s[28:29]
	v_cndmask_b32_e64 v216, v217, 1.0, s[28:29]
	v_pk_mul_f32 v[222:223], v[182:183], v[216:217] op_sel_hi:[1,0]
	v_sub_f32_e32 v145, v145, v192
	v_sub_f32_e32 v144, v144, v192
	v_pk_mul_f32 v[230:231], v[180:181], v[216:217] op_sel_hi:[1,0]
	v_sub_f32_e32 v147, v147, v192
	v_sub_f32_e32 v146, v146, v192
	v_pk_fma_f32 v[120:121], v[222:223], v[144:145], v[120:121]
	v_add_co_u32_e32 v144, vcc, s40, v170
	v_pk_fma_f32 v[122:123], v[230:231], v[146:147], v[122:123]
	s_nop 0
	v_addc_co_u32_e32 v145, vcc, 0, v171, vcc
	global_store_dwordx4 v[144:145], v[120:123], off
	v_sub_f32_e32 v137, v137, v192
	v_sub_f32_e32 v136, v136, v192
	v_pk_mul_f32 v[120:121], v[174:175], v[216:217] op_sel_hi:[1,0]
	v_pk_mul_f32 v[122:123], v[184:185], v[216:217] op_sel_hi:[1,0]
	v_sub_f32_e32 v139, v139, v192
	v_sub_f32_e32 v138, v138, v192
	v_pk_fma_f32 v[118:119], v[122:123], v[138:139], v[118:119]
	v_pk_fma_f32 v[116:117], v[120:121], v[136:137], v[116:117]
	s_mov_b64 s[40:41], 0x100000
	global_store_dwordx4 v[144:145], v[116:119], off offset:16
	v_cndmask_b32_e64 v192, v214, 0, s[28:29]
	v_cndmask_b32_e64 v214, v215, 1.0, s[28:29]
	v_lshl_add_u64 v[116:117], v[164:165], 0, s[40:41]
	s_mov_b32 s40, 0x100000
	v_add_co_u32_e32 v138, vcc, s40, v164
	v_pk_mul_f32 v[136:137], v[182:183], v[214:215] op_sel_hi:[1,0]
	s_nop 0
	v_addc_co_u32_e32 v139, vcc, 0, v165, vcc
	global_load_dwordx4 v[120:123], v[138:139], off
	s_nop 0
	global_load_dwordx4 v[116:119], v[116:117], off offset:16
	s_nop 0
	global_load_dwordx2 v[146:147], v[162:163], off offset:1024
	v_sub_f32_e32 v141, v141, v192
	v_sub_f32_e32 v140, v140, v192
	v_pk_mul_f32 v[216:217], v[180:181], v[214:215] op_sel_hi:[1,0]
	v_sub_f32_e32 v143, v143, v192
	v_sub_f32_e32 v142, v142, v192
	v_pk_fma_f32 v[112:113], v[136:137], v[140:141], v[112:113]
	v_add_co_u32_e32 v136, vcc, s42, v170
	v_pk_fma_f32 v[114:115], v[216:217], v[142:143], v[114:115]
	s_nop 0
	v_addc_co_u32_e32 v137, vcc, 0, v171, vcc
	global_store_dwordx4 v[136:137], v[112:115], off
	v_sub_f32_e32 v133, v133, v192
	v_sub_f32_e32 v132, v132, v192
	v_pk_mul_f32 v[112:113], v[174:175], v[214:215] op_sel_hi:[1,0]
	s_mov_b32 s41, 0x120000
	v_pk_mul_f32 v[114:115], v[184:185], v[214:215] op_sel_hi:[1,0]
	v_sub_f32_e32 v135, v135, v192
	v_sub_f32_e32 v134, v134, v192
	v_pk_fma_f32 v[108:109], v[112:113], v[132:133], v[108:109]
	v_add_co_u32_e32 v132, vcc, s41, v164
	v_pk_fma_f32 v[110:111], v[114:115], v[134:135], v[110:111]
	s_nop 0
	v_addc_co_u32_e32 v133, vcc, 0, v165, vcc
	global_store_dwordx4 v[136:137], v[108:111], off offset:16
	s_mov_b64 s[74:75], 0x120000
	s_waitcnt vmcnt(0)
	v_cndmask_b32_e64 v141, v150, 0, s[28:29]
	v_cndmask_b32_e64 v140, v151, 1.0, s[28:29]
	v_pk_mul_f32 v[142:143], v[182:183], v[140:141] op_sel_hi:[1,0]
	v_sub_f32_e32 v129, v129, v141
	v_sub_f32_e32 v128, v128, v141
	v_pk_mul_f32 v[150:151], v[180:181], v[140:141] op_sel_hi:[1,0]
	v_sub_f32_e32 v131, v131, v141
	v_sub_f32_e32 v130, v130, v141
	v_pk_fma_f32 v[128:129], v[142:143], v[128:129], v[104:105]
	v_add_co_u32_e32 v104, vcc, s43, v170
	v_lshl_add_u64 v[108:109], v[164:165], 0, s[74:75]
	v_pk_fma_f32 v[130:131], v[150:151], v[130:131], v[106:107]
	v_addc_co_u32_e32 v105, vcc, 0, v171, vcc
	global_load_dwordx4 v[112:115], v[132:133], off
	s_nop 0
	global_load_dwordx4 v[108:111], v[108:109], off offset:16
	s_nop 0
	global_load_dwordx2 v[134:135], v[162:163], off offset:1152
	global_store_dwordx4 v[104:105], v[128:131], off
	v_pk_mul_f32 v[106:107], v[174:175], v[140:141] op_sel_hi:[1,0]
	v_sub_f32_e32 v125, v125, v141
	v_pk_mul_f32 v[128:129], v[184:185], v[140:141] op_sel_hi:[1,0]
	v_sub_f32_e32 v124, v124, v141
	v_sub_f32_e32 v127, v127, v141
	v_sub_f32_e32 v126, v126, v141
	v_pk_fma_f32 v[102:103], v[128:129], v[126:127], v[102:103]
	v_pk_fma_f32 v[100:101], v[106:107], v[124:125], v[100:101]
	s_mov_b64 s[42:43], 0x140000
	global_store_dwordx4 v[104:105], v[100:103], off offset:16
	s_mov_b64 s[74:75], 0x160000
	v_cndmask_b32_e64 v146, v146, 0, s[28:29]
	v_lshl_add_u64 v[102:103], v[164:165], 0, s[42:43]
	s_mov_b32 s42, 0x140000
	v_add_co_u32_e32 v100, vcc, s42, v164
	v_cndmask_b32_e64 v106, v147, 1.0, s[28:29]
	s_nop 0
	v_addc_co_u32_e32 v101, vcc, 0, v165, vcc
	global_load_dwordx4 v[124:127], v[100:101], off
	global_load_dwordx4 v[128:131], v[102:103], off offset:16
	s_nop 0
	global_load_dwordx2 v[102:103], v[162:163], off offset:1280
	v_pk_mul_f32 v[140:141], v[182:183], v[106:107] op_sel_hi:[1,0]
	v_pk_mul_f32 v[142:143], v[180:181], v[106:107] op_sel_hi:[1,0]
	v_sub_f32_e32 v121, v121, v146
	v_sub_f32_e32 v120, v120, v146
	v_sub_f32_e32 v123, v123, v146
	v_sub_f32_e32 v122, v122, v146
	v_pk_fma_f32 v[122:123], v[142:143], v[122:123], v[98:99]
	v_pk_fma_f32 v[120:121], v[140:141], v[120:121], v[96:97]
	v_add_co_u32_e32 v96, vcc, s40, v170
	v_pk_mul_f32 v[98:99], v[174:175], v[106:107] op_sel_hi:[1,0]
	v_pk_mul_f32 v[106:107], v[184:185], v[106:107] op_sel_hi:[1,0]
	v_sub_f32_e32 v117, v117, v146
	v_sub_f32_e32 v116, v116, v146
	v_sub_f32_e32 v119, v119, v146
	v_sub_f32_e32 v118, v118, v146
	v_addc_co_u32_e32 v97, vcc, 0, v171, vcc
	v_pk_fma_f32 v[94:95], v[106:107], v[118:119], v[94:95]
	v_pk_fma_f32 v[92:93], v[98:99], v[116:117], v[92:93]
	s_mov_b32 s40, 0x160000
	global_store_dwordx4 v[96:97], v[120:123], off
	global_store_dwordx4 v[96:97], v[92:95], off offset:16
	s_waitcnt vmcnt(0)
; #define RES_LOADG(slot, g_) do { const int ro_ = ((g_) >> 2) * HALF + ((g_) & 3) * 16; \
;                 _Pragma("unroll") for (int n = 0; n < 2; ++n) xa[slot][n] = *(const f32x4*)(sl + rbase + (size_t)ro_ * 2048 + bj * HALF + 4 * n); \
;                 ms[slot] = *(const f2_t_*)(stp + 2 * (row0 + ro_)); } while (0)
;     __device__ __forceinline__ void operator()(const f32x4 (&acc)[2][2][4][2], const Unit& u, int wr, int wc, int fr, int fq) const {
;     ...
; #pragma unroll
;         for (int bj = 0; bj < 2; ++bj) {
;             f32x4 mv[2], ag[2], ab[2];
; #pragma unroll
;             for (int n = 0; n < 2; ++n) { mv[n] = *(const f32x4*)(mp + col0 + bj * HALF + 4 * n) * coef;
;                 const f32x4 g4 = *(const f32x4*)(lg + col0 + bj * HALF + 4 * n), b4 = *(const f32x4*)(lb + col0 + bj * HALF + 4 * n);
;                 const f32x4 g4s = ln ? g4 : (f32x4){1.f, 1.f, 1.f, 1.f}, b4s = ln ? b4 : (f32x4){0.f, 0.f, 0.f, 0.f};
;                 ag[n] = g4s * al; ab[n] = b4s * al; }
;             f32x4 xa[3][2]; f2_t_ ms[3];
;     ...
;             RES_LOADG(0, 0); RES_LOADG(1, 1);
	v_cndmask_b32_e64 v140, v134, 0, s[28:29]
	v_add_co_u32_e32 v92, vcc, s40, v164
	v_lshl_add_u64 v[94:95], v[164:165], 0, s[74:75]
	s_nop 0
	v_addc_co_u32_e32 v93, vcc, 0, v165, vcc
	global_load_dwordx4 v[116:119], v[92:93], off
	global_load_dwordx4 v[120:123], v[94:95], off offset:16
	s_nop 0
	global_load_dwordx2 v[94:95], v[162:163], off offset:1408
	v_cndmask_b32_e64 v98, v135, 1.0, s[28:29]
	v_pk_mul_f32 v[106:107], v[182:183], v[98:99] op_sel_hi:[1,0]
	v_pk_mul_f32 v[134:135], v[180:181], v[98:99] op_sel_hi:[1,0]
	v_sub_f32_e32 v113, v113, v140
	v_sub_f32_e32 v112, v112, v140
	v_sub_f32_e32 v115, v115, v140
	v_sub_f32_e32 v114, v114, v140
	v_pk_fma_f32 v[114:115], v[134:135], v[114:115], v[90:91]
	v_pk_fma_f32 v[112:113], v[106:107], v[112:113], v[88:89]
	v_add_co_u32_e32 v88, vcc, s41, v170
	v_pk_mul_f32 v[90:91], v[174:175], v[98:99] op_sel_hi:[1,0]
	v_pk_mul_f32 v[98:99], v[184:185], v[98:99] op_sel_hi:[1,0]
	v_sub_f32_e32 v107, v109, v140
	v_sub_f32_e32 v106, v108, v140
	v_sub_f32_e32 v109, v111, v140
	v_sub_f32_e32 v108, v110, v140
	v_addc_co_u32_e32 v89, vcc, 0, v171, vcc
	v_pk_fma_f32 v[86:87], v[98:99], v[108:109], v[86:87]
	v_pk_fma_f32 v[84:85], v[90:91], v[106:107], v[84:85]
	global_store_dwordx4 v[88:89], v[84:87], off offset:16
	v_cndmask_b32_e64 v106, v102, 0, s[28:29]
	v_sub_f32_e32 v99, v125, v106
	v_cndmask_b32_e64 v86, v103, 1.0, s[28:29]
	v_pk_mul_f32 v[84:85], v[182:183], v[86:87] op_sel_hi:[1,0]
	v_sub_f32_e32 v98, v124, v106
	global_store_dwordx4 v[88:89], v[112:115], off
	v_pk_mul_f32 v[90:91], v[180:181], v[86:87] op_sel_hi:[1,0]
	v_sub_f32_e32 v103, v127, v106
	v_sub_f32_e32 v102, v126, v106
	v_pk_fma_f32 v[80:81], v[84:85], v[98:99], v[80:81]
	v_add_co_u32_e32 v84, vcc, s42, v170
	v_pk_fma_f32 v[82:83], v[90:91], v[102:103], v[82:83]
	s_nop 0
	v_addc_co_u32_e32 v85, vcc, 0, v171, vcc
	global_store_dwordx4 v[84:85], v[80:83], off
	v_sub_f32_e32 v91, v131, v106
	v_sub_f32_e32 v90, v130, v106
	v_pk_mul_f32 v[80:81], v[174:175], v[86:87] op_sel_hi:[1,0]
	v_pk_mul_f32 v[82:83], v[184:185], v[86:87] op_sel_hi:[1,0]
	v_sub_f32_e32 v87, v129, v106
	v_sub_f32_e32 v86, v128, v106
	v_pk_fma_f32 v[78:79], v[82:83], v[90:91], v[78:79]
	v_pk_fma_f32 v[76:77], v[80:81], v[86:87], v[76:77]
	global_store_dwordx4 v[84:85], v[76:79], off offset:16
	v_mov_b32_e32 v91, 0x3fb504f3
	s_waitcnt vmcnt(0)
	v_cndmask_b32_e64 v90, v94, 0, s[28:29]
	v_cndmask_b32_e64 v76, v95, 1.0, s[28:29]
	v_pk_mul_f32 v[80:81], v[180:181], v[76:77] op_sel_hi:[1,0]
	v_sub_f32_e32 v87, v119, v90
	v_sub_f32_e32 v86, v118, v90
	v_pk_mul_f32 v[78:79], v[182:183], v[76:77] op_sel_hi:[1,0]
	v_sub_f32_e32 v83, v117, v90
	v_sub_f32_e32 v82, v116, v90
	v_pk_fma_f32 v[74:75], v[80:81], v[86:87], v[74:75]
	v_add_co_u32_e32 v86, vcc, s40, v170
	v_pk_fma_f32 v[72:73], v[78:79], v[82:83], v[72:73]
	s_nop 0
	v_addc_co_u32_e32 v87, vcc, 0, v171, vcc
	global_store_dwordx4 v[86:87], v[72:75], off
	v_sub_f32_e32 v79, v123, v90
	v_sub_f32_e32 v78, v122, v90
	v_pk_mul_f32 v[72:73], v[174:175], v[76:77] op_sel_hi:[1,0]
	v_pk_mul_f32 v[74:75], v[184:185], v[76:77] op_sel_hi:[1,0]
	v_sub_f32_e32 v77, v121, v90
	v_sub_f32_e32 v76, v120, v90
	v_pk_fma_f32 v[70:71], v[74:75], v[78:79], v[70:71]
	v_pk_fma_f32 v[68:69], v[72:73], v[76:77], v[68:69]
	global_store_dwordx4 v[86:87], v[68:71], off offset:16
	global_load_dwordx4 v[68:71], v[172:173], off offset:512
	global_load_dwordx4 v[80:83], v[166:167], off offset:512
	s_mov_b32 s40, 0x3fb504f3
	v_mov_b32_e32 v90, 0x3fb504f3
	s_and_b64 vcc, exec, s[4:5]
	v_mov_b32_e32 v94, 0x3fb504f3
	v_mov_b32_e32 v95, 0x3fb504f3
	global_load_dwordx4 v[76:79], v[172:173], off offset:528
	global_load_dwordx4 v[72:75], v[166:167], off offset:528
	s_cbranch_vccnz .LBB0_333
	global_load_dwordx4 v[244:247], v[168:169], off offset:512
	global_load_dwordx4 v[106:109], v[168:169], off offset:528
	s_waitcnt vmcnt(0)
	v_pk_mul_f32 v[94:95], v[246:247], s[40:41] op_sel_hi:[1,0]
	v_pk_mul_f32 v[90:91], v[244:245], s[40:41] op_sel_hi:[1,0]
	v_pk_mul_f32 v[102:103], v[82:83], s[40:41] op_sel_hi:[1,0]
	v_pk_mul_f32 v[98:99], v[80:81], s[40:41] op_sel_hi:[1,0]
	v_pk_mul_f32 v[82:83], v[108:109], s[40:41] op_sel_hi:[1,0]
	v_pk_mul_f32 v[80:81], v[106:107], s[40:41] op_sel_hi:[1,0]
	s_branch .LBB0_334
.LBB0_331:
.LBB0_333:
	s_waitcnt vmcnt(0)
	v_mov_b32_e32 v80, 0x3fb504f3
	v_mov_b32_e32 v98, 0
	v_mov_b32_e32 v99, v98
	v_mov_b32_e32 v102, v98
	v_mov_b32_e32 v103, v98
	v_mov_b32_e32 v81, v80
	v_mov_b32_e32 v82, v80
	v_mov_b32_e32 v83, v80

; #define RES_LOADG(slot, g_) do { const int ro_ = ((g_) >> 2) * HALF + ((g_) & 3) * 16; \
;                 _Pragma("unroll") for (int n = 0; n < 2; ++n) xa[slot][n] = *(const f32x4*)(sl + rbase + (size_t)ro_ * 2048 + bj * HALF + 4 * n); \
;                 ms[slot] = *(const f2_t_*)(stp + 2 * (row0 + ro_)); } while (0)
;     __device__ __forceinline__ void operator()(const f32x4 (&acc)[2][2][4][2], const Unit& u, int wr, int wc, int fr, int fq) const {
;     ...
; #pragma unroll
;         for (int bj = 0; bj < 2; ++bj) {
;             f32x4 mv[2], ag[2], ab[2];
; #pragma unroll
;             for (int n = 0; n < 2; ++n) { mv[n] = *(const f32x4*)(mp + col0 + bj * HALF + 4 * n) * coef;
;                 const f32x4 g4 = *(const f32x4*)(lg + col0 + bj * HALF + 4 * n), b4 = *(const f32x4*)(lb + col0 + bj * HALF + 4 * n);
;                 const f32x4 g4s = ln ? g4 : (f32x4){1.f, 1.f, 1.f, 1.f}, b4s = ln ? b4 : (f32x4){0.f, 0.f, 0.f, 0.f};
;                 ag[n] = g4s * al; ab[n] = b4s * al; }
;             f32x4 xa[3][2]; f2_t_ ms[3];
;     ...
;             RES_LOADG(0, 0); RES_LOADG(1, 1);
.LBB0_1074:
	s_ashr_i32 s4, s73, 3
	s_mul_hi_i32 s5, s4, 0x12000
	s_mul_i32 s4, s4, 0x12000
	v_lshl_or_b32 v148, s74, 8, v218
	s_add_u32 s4, s55, s4
	v_ashrrev_i32_e32 v149, 31, v148
	s_addc_u32 s5, s58, s5
	v_lshlrev_b64 v[122:123], 2, v[148:149]
	v_lshl_add_u64 v[120:121], s[4:5], 0, v[122:123]
	v_add_co_u32_e32 v116, vcc, 0xa000, v120
	v_lshl_add_u64 v[178:179], s[6:7], 0, v[122:123]
	s_nop 0
	v_addc_co_u32_e32 v117, vcc, 0, v121, vcc
	global_load_dwordx4 v[116:119], v[116:117], off
	s_nop 0
	global_load_dwordx4 v[144:147], v[178:179], off
	v_lshl_add_u64 v[180:181], s[20:21], 0, v[122:123]
	v_cndmask_b32_e64 v122, 0, 1, s[26:27]
	v_mov_b32_e32 v184, 0x3fb504f3
	v_cmp_ne_u32_e64 s[4:5], 1, v122
	s_andn2_b64 vcc, exec, s[26:27]
	v_mov_b32_e32 v188, 0x3fb504f3
	v_mov_b32_e32 v189, 0x3fb504f3
	v_mov_b32_e32 v186, 0x3fb504f3
	v_mov_b32_e32 v187, 0x3fb504f3
	s_mov_b64 s[38:39], 0xa000
	v_lshl_add_u64 v[182:183], v[120:121], 0, s[38:39]
	global_load_dwordx4 v[120:123], v[182:183], off offset:16
	global_load_dwordx4 v[140:143], v[178:179], off offset:16
	v_mov_b32_e32 v185, 0x3fb504f3
	v_mov_b32_e32 v190, 0x3fb504f3
	v_mov_b32_e32 v191, 0x3fb504f3
	s_cbranch_vccnz .LBB0_1078
	global_load_dwordx4 v[244:247], v[180:181], off
	global_load_dwordx4 v[150:153], v[180:181], off offset:16
	s_waitcnt vmcnt(0)
	v_pk_mul_f32 v[186:187], v[246:247], s[40:41] op_sel_hi:[1,0]
	v_pk_mul_f32 v[188:189], v[244:245], s[40:41] op_sel_hi:[1,0]
	v_pk_mul_f32 v[190:191], v[152:153], s[40:41] op_sel_hi:[1,0]
	v_pk_mul_f32 v[184:185], v[150:151], s[40:41] op_sel_hi:[1,0]
.LBB0_1076:
.LBB0_1078:
	s_waitcnt vmcnt(0)
	v_pk_mul_f32 v[144:145], v[144:145], s[40:41] op_sel_hi:[1,0]
	v_pk_mul_f32 v[140:141], v[140:141], s[40:41] op_sel_hi:[1,0]
	v_cndmask_b32_e64 v204, v144, 0, s[28:29]
	v_lshl_add_u32 v144, s73, 8, v216
	v_cndmask_b32_e64 v205, v145, 0, s[28:29]
	v_ashrrev_i32_e32 v145, 31, v144
	v_cndmask_b32_e64 v209, v141, 0, s[28:29]
	v_cndmask_b32_e64 v208, v140, 0, s[28:29]
	v_lshlrev_b64 v[140:141], 13, v[144:145]
	v_lshl_add_u64 v[140:141], s[8:9], 0, v[140:141]
	v_lshl_add_u64 v[172:173], v[148:149], 2, v[140:141]
	s_mov_b64 s[38:39], 0x20000
	v_pk_mul_f32 v[146:147], v[146:147], s[40:41] op_sel_hi:[1,0]
	v_lshl_add_u64 v[140:141], v[172:173], 0, s[38:39]
	s_mov_b32 s38, 0x20000
	v_cndmask_b32_e64 v206, v146, 0, s[28:29]
	v_lshlrev_b32_e32 v146, 1, v144
	v_add_co_u32_e32 v176, vcc, s38, v172
	v_cndmask_b32_e64 v207, v147, 0, s[28:29]
	v_ashrrev_i32_e32 v147, 31, v146
	v_addc_co_u32_e32 v177, vcc, 0, v173, vcc
	v_lshl_add_u64 v[170:171], v[146:147], 2, s[30:31]
	global_load_dwordx4 v[156:159], v[172:173], off offset:16
	global_load_dwordx4 v[220:223], v[172:173], off
	global_load_dwordx4 v[152:155], v[176:177], off
	global_load_dwordx4 v[148:151], v[140:141], off offset:16
	global_load_dwordx2 v[192:193], v[170:171], off
	global_load_dwordx2 v[214:215], v[170:171], off offset:128
	s_mov_b64 s[38:39], 0x40000
	v_lshl_add_u64 v[140:141], v[172:173], 0, s[38:39]
	s_mov_b32 s38, 0x40000
	v_pk_mul_f32 v[142:143], v[142:143], s[40:41] op_sel_hi:[1,0]
	v_add_co_u32_e32 v174, vcc, s38, v172
	v_pk_fma_f32 v[138:139], v[138:139], v[118:119], v[206:207]
	v_pk_fma_f32 v[136:137], v[136:137], v[116:117], v[204:205]
	v_cndmask_b32_e64 v211, v143, 0, s[28:29]
	v_cndmask_b32_e64 v210, v142, 0, s[28:29]
	v_addc_co_u32_e32 v175, vcc, 0, v173, vcc
	global_load_dwordx4 v[144:147], v[174:175], off
	s_nop 0
	global_load_dwordx4 v[140:143], v[140:141], off offset:16
	s_nop 0
	global_load_dwordx2 v[212:213], v[170:171], off offset:256
	v_pk_fma_f32 v[134:135], v[134:135], v[122:123], v[210:211]
	v_pk_fma_f32 v[132:133], v[132:133], v[120:121], v[208:209]
	s_mov_b64 s[38:39], 0x60000
	v_pk_fma_f32 v[130:131], v[130:131], v[118:119], v[206:207]
	v_pk_fma_f32 v[128:129], v[128:129], v[116:117], v[204:205]
	v_pk_fma_f32 v[126:127], v[126:127], v[122:123], v[210:211]
	v_pk_fma_f32 v[124:125], v[124:125], v[120:121], v[208:209]
	v_pk_fma_f32 v[114:115], v[114:115], v[118:119], v[206:207]
	v_pk_fma_f32 v[112:113], v[112:113], v[116:117], v[204:205]
	v_pk_fma_f32 v[110:111], v[110:111], v[122:123], v[210:211]
	v_pk_fma_f32 v[108:109], v[108:109], v[120:121], v[208:209]
	v_pk_fma_f32 v[106:107], v[106:107], v[118:119], v[206:207]
	v_pk_fma_f32 v[104:105], v[104:105], v[116:117], v[204:205]
	v_pk_fma_f32 v[102:103], v[102:103], v[122:123], v[210:211]
	v_pk_fma_f32 v[100:101], v[100:101], v[120:121], v[208:209]
	v_pk_fma_f32 v[98:99], v[98:99], v[118:119], v[206:207]
	v_pk_fma_f32 v[96:97], v[96:97], v[116:117], v[204:205]
	v_pk_fma_f32 v[94:95], v[94:95], v[122:123], v[210:211]
	v_pk_fma_f32 v[92:93], v[92:93], v[120:121], v[208:209]
	v_pk_fma_f32 v[90:91], v[90:91], v[118:119], v[206:207]
	v_pk_fma_f32 v[88:89], v[88:89], v[116:117], v[204:205]
	v_pk_fma_f32 v[86:87], v[86:87], v[122:123], v[210:211]
	v_pk_fma_f32 v[84:85], v[84:85], v[120:121], v[208:209]
	v_pk_fma_f32 v[82:83], v[82:83], v[118:119], v[206:207]
	v_pk_fma_f32 v[80:81], v[80:81], v[116:117], v[204:205]
	v_pk_fma_f32 v[78:79], v[78:79], v[122:123], v[210:211]
	v_pk_fma_f32 v[76:77], v[76:77], v[120:121], v[208:209]
	v_pk_fma_f32 v[74:75], v[74:75], v[118:119], v[206:207]
	v_pk_fma_f32 v[72:73], v[72:73], v[116:117], v[204:205]
	v_pk_fma_f32 v[70:71], v[70:71], v[122:123], v[210:211]
	v_pk_fma_f32 v[68:69], v[68:69], v[120:121], v[208:209]
	s_waitcnt vmcnt(0)
; #define RES_LOADG(slot, g_) do { const int ro_ = ((g_) >> 2) * HALF + ((g_) & 3) * 16; \
;                 _Pragma("unroll") for (int n = 0; n < 2; ++n) xa[slot][n] = *(const f32x4*)(sl + rbase + (size_t)ro_ * 2048 + bj * HALF + 4 * n); \
;                 ms[slot] = *(const f2_t_*)(stp + 2 * (row0 + ro_)); } while (0)
;     __device__ __forceinline__ void operator()(const f32x4 (&acc)[2][2][4][2], const Unit& u, int wr, int wc, int fr, int fq) const {
;     ...
; #pragma unroll
;             for (int gi = 0; gi < 8; ++gi) {
;                 const int ai = gi >> 2, m = gi & 3;
;                 if (gi + 2 < 8) RES_LOADG((gi + 2) % 3, gi + 2);
;                 asm volatile("" ::: "memory");
;                 float* rowp = xl + rbase + (size_t)(ai * HALF + m * 16) * 2048 + bj * HALF;
;                 const float mean = ln ? ms[gi % 3][0] : 0.f, rstd = ln ? ms[gi % 3][1] : 1.f;
; #pragma unroll
;                 for (int n = 0; n < 2; ++n) { const f32x4 t = ag[n] * rstd;
;                     *(f32x4*)(rowp + 4 * n) = (xa[gi % 3][n] - mean) * t + (ab[n] + mv[n] * acc[ai][bj][m][n]); }
;                 asm volatile("" ::: "memory");
;             }
	v_cndmask_b32_e64 v228, v192, 0, s[28:29]
	v_cndmask_b32_e64 v192, v193, 1.0, s[28:29]
	v_pk_mul_f32 v[196:197], v[188:189], v[192:193] op_sel_hi:[1,0]
	v_pk_mul_f32 v[198:199], v[186:187], v[192:193] op_sel_hi:[1,0]
	v_sub_f32_e32 v201, v221, v228
	v_sub_f32_e32 v200, v220, v228
	v_sub_f32_e32 v203, v223, v228
	v_sub_f32_e32 v202, v222, v228
	v_pk_fma_f32 v[138:139], v[198:199], v[202:203], v[138:139]
	v_pk_fma_f32 v[136:137], v[196:197], v[200:201], v[136:137]
	global_store_dwordx4 v[172:173], v[136:139], off
	v_sub_f32_e32 v157, v157, v228
	v_sub_f32_e32 v156, v156, v228
	v_pk_mul_f32 v[136:137], v[184:185], v[192:193] op_sel_hi:[1,0]
	v_pk_mul_f32 v[138:139], v[190:191], v[192:193] op_sel_hi:[1,0]
	v_sub_f32_e32 v159, v159, v228
	v_sub_f32_e32 v158, v158, v228
	v_pk_fma_f32 v[134:135], v[138:139], v[158:159], v[134:135]
	v_pk_fma_f32 v[132:133], v[136:137], v[156:157], v[132:133]
	global_store_dwordx4 v[172:173], v[132:135], off offset:16
	v_cndmask_b32_e64 v193, v214, 0, s[28:29]
	v_cndmask_b32_e64 v192, v215, 1.0, s[28:29]
	v_lshl_add_u64 v[132:133], v[172:173], 0, s[38:39]
	s_mov_b32 s38, 0x60000
	v_add_co_u32_e32 v156, vcc, s38, v172
	v_pk_mul_f32 v[196:197], v[188:189], v[192:193] op_sel_hi:[1,0]
	v_pk_mul_f32 v[198:199], v[186:187], v[192:193] op_sel_hi:[1,0]
	v_sub_f32_e32 v153, v153, v193
	v_sub_f32_e32 v152, v152, v193
	v_sub_f32_e32 v155, v155, v193
	v_sub_f32_e32 v154, v154, v193
	v_addc_co_u32_e32 v157, vcc, 0, v173, vcc
	v_pk_fma_f32 v[130:131], v[198:199], v[154:155], v[130:131]
	v_pk_fma_f32 v[128:129], v[196:197], v[152:153], v[128:129]
	global_load_dwordx4 v[136:139], v[156:157], off
	s_nop 0
	global_load_dwordx4 v[132:135], v[132:133], off offset:16
	s_nop 0
	global_load_dwordx2 v[158:159], v[170:171], off offset:384
	global_store_dwordx4 v[176:177], v[128:131], off
	v_pk_mul_f32 v[152:153], v[190:191], v[192:193] op_sel_hi:[1,0]
	s_mov_b64 s[38:39], 0x100000
	v_pk_mul_f32 v[128:129], v[184:185], v[192:193] op_sel_hi:[1,0]
	v_sub_f32_e32 v131, v149, v193
	v_sub_f32_e32 v130, v148, v193
	v_sub_f32_e32 v149, v151, v193
	v_sub_f32_e32 v148, v150, v193
	v_pk_fma_f32 v[126:127], v[152:153], v[148:149], v[126:127]
	v_pk_fma_f32 v[124:125], v[128:129], v[130:131], v[124:125]
	global_store_dwordx4 v[176:177], v[124:127], off offset:16
	v_cndmask_b32_e64 v153, v212, 0, s[28:29]
	v_cndmask_b32_e64 v152, v213, 1.0, s[28:29]
	v_lshl_add_u64 v[124:125], v[172:173], 0, s[38:39]
	s_mov_b32 s38, 0x100000
	v_add_co_u32_e32 v148, vcc, s38, v172
	v_pk_mul_f32 v[154:155], v[188:189], v[152:153] op_sel_hi:[1,0]
	s_nop 0
	v_addc_co_u32_e32 v149, vcc, 0, v173, vcc
	global_load_dwordx4 v[128:131], v[148:149], off
	s_nop 0
	global_load_dwordx4 v[124:127], v[124:125], off offset:16
	s_nop 0
	global_load_dwordx2 v[150:151], v[170:171], off offset:1024
	v_pk_mul_f32 v[192:193], v[186:187], v[152:153] op_sel_hi:[1,0]
	v_sub_f32_e32 v145, v145, v153
	v_sub_f32_e32 v144, v144, v153
	v_sub_f32_e32 v147, v147, v153
	v_sub_f32_e32 v146, v146, v153
	v_pk_fma_f32 v[114:115], v[192:193], v[146:147], v[114:115]
	v_pk_fma_f32 v[112:113], v[154:155], v[144:145], v[112:113]
	global_store_dwordx4 v[174:175], v[112:115], off
	v_sub_f32_e32 v141, v141, v153
	v_sub_f32_e32 v140, v140, v153
	v_pk_mul_f32 v[112:113], v[184:185], v[152:153] op_sel_hi:[1,0]
	v_pk_mul_f32 v[114:115], v[190:191], v[152:153] op_sel_hi:[1,0]
	v_sub_f32_e32 v143, v143, v153
	v_sub_f32_e32 v142, v142, v153
	v_pk_fma_f32 v[110:111], v[114:115], v[142:143], v[110:111]
	v_pk_fma_f32 v[108:109], v[112:113], v[140:141], v[108:109]
	s_mov_b64 s[38:39], 0x120000
	global_store_dwordx4 v[174:175], v[108:111], off offset:16
	s_waitcnt vmcnt(0)
	v_cndmask_b32_e64 v145, v158, 0, s[28:29]
	v_lshl_add_u64 v[108:109], v[172:173], 0, s[38:39]
	s_mov_b32 s38, 0x120000
	v_cndmask_b32_e64 v144, v159, 1.0, s[28:29]
	v_add_co_u32_e32 v140, vcc, s38, v172
	v_pk_mul_f32 v[146:147], v[188:189], v[144:145] op_sel_hi:[1,0]
	v_pk_mul_f32 v[152:153], v[186:187], v[144:145] op_sel_hi:[1,0]
	v_sub_f32_e32 v137, v137, v145
	v_sub_f32_e32 v136, v136, v145
	v_sub_f32_e32 v139, v139, v145
	v_sub_f32_e32 v138, v138, v145
	v_addc_co_u32_e32 v141, vcc, 0, v173, vcc
	v_pk_fma_f32 v[106:107], v[152:153], v[138:139], v[106:107]
	v_pk_fma_f32 v[104:105], v[146:147], v[136:137], v[104:105]
	global_load_dwordx4 v[112:115], v[140:141], off
	s_nop 0
	global_load_dwordx4 v[108:111], v[108:109], off offset:16
	s_nop 0
	global_load_dwordx2 v[142:143], v[170:171], off offset:1152
	global_store_dwordx4 v[156:157], v[104:107], off
	v_sub_f32_e32 v133, v133, v145
	v_sub_f32_e32 v132, v132, v145
	v_pk_mul_f32 v[104:105], v[184:185], v[144:145] op_sel_hi:[1,0]
	v_pk_mul_f32 v[106:107], v[190:191], v[144:145] op_sel_hi:[1,0]
	v_sub_f32_e32 v135, v135, v145
	v_sub_f32_e32 v134, v134, v145
	v_pk_fma_f32 v[102:103], v[106:107], v[134:135], v[102:103]
	v_pk_fma_f32 v[100:101], v[104:105], v[132:133], v[100:101]
	s_mov_b64 s[38:39], 0x140000
	global_store_dwordx4 v[156:157], v[100:103], off offset:16
	v_cndmask_b32_e64 v146, v150, 0, s[28:29]
	v_cndmask_b32_e64 v106, v151, 1.0, s[28:29]
	v_lshl_add_u64 v[100:101], v[172:173], 0, s[38:39]
	s_mov_b32 s38, 0x140000
	v_add_co_u32_e32 v104, vcc, s38, v172
	v_pk_mul_f32 v[138:139], v[188:189], v[106:107] op_sel_hi:[1,0]
	v_pk_mul_f32 v[144:145], v[186:187], v[106:107] op_sel_hi:[1,0]
	v_sub_f32_e32 v129, v129, v146
	v_sub_f32_e32 v128, v128, v146
	v_sub_f32_e32 v131, v131, v146
	v_sub_f32_e32 v130, v130, v146
	v_addc_co_u32_e32 v105, vcc, 0, v173, vcc
	v_pk_fma_f32 v[98:99], v[144:145], v[130:131], v[98:99]
	v_pk_fma_f32 v[96:97], v[138:139], v[128:129], v[96:97]
	global_load_dwordx4 v[132:135], v[104:105], off
	s_nop 0
	global_load_dwordx4 v[100:103], v[100:101], off offset:16
	s_nop 0
	global_load_dwordx2 v[136:137], v[170:171], off offset:1280
	global_store_dwordx4 v[148:149], v[96:99], off
	s_mov_b64 s[38:39], 0x160000
	s_nop 0
	v_pk_mul_f32 v[96:97], v[184:185], v[106:107] op_sel_hi:[1,0]
	v_pk_mul_f32 v[98:99], v[190:191], v[106:107] op_sel_hi:[1,0]
	v_sub_f32_e32 v107, v125, v146
	v_sub_f32_e32 v106, v124, v146
	v_sub_f32_e32 v125, v127, v146
	v_sub_f32_e32 v124, v126, v146
	v_pk_fma_f32 v[94:95], v[98:99], v[124:125], v[94:95]
	v_pk_fma_f32 v[92:93], v[96:97], v[106:107], v[92:93]
	global_store_dwordx4 v[148:149], v[92:95], off offset:16
	s_waitcnt vmcnt(0)
; #define RES_LOADG(slot, g_) do { const int ro_ = ((g_) >> 2) * HALF + ((g_) & 3) * 16; \
;                 _Pragma("unroll") for (int n = 0; n < 2; ++n) xa[slot][n] = *(const f32x4*)(sl + rbase + (size_t)ro_ * 2048 + bj * HALF + 4 * n); \
;                 ms[slot] = *(const f2_t_*)(stp + 2 * (row0 + ro_)); } while (0)
;     __device__ __forceinline__ void operator()(const f32x4 (&acc)[2][2][4][2], const Unit& u, int wr, int wc, int fr, int fq) const {
;     ...
; #pragma unroll
;         for (int bj = 0; bj < 2; ++bj) {
;             f32x4 mv[2], ag[2], ab[2];
; #pragma unroll
;             for (int n = 0; n < 2; ++n) { mv[n] = *(const f32x4*)(mp + col0 + bj * HALF + 4 * n) * coef;
;                 const f32x4 g4 = *(const f32x4*)(lg + col0 + bj * HALF + 4 * n), b4 = *(const f32x4*)(lb + col0 + bj * HALF + 4 * n);
;                 const f32x4 g4s = ln ? g4 : (f32x4){1.f, 1.f, 1.f, 1.f}, b4s = ln ? b4 : (f32x4){0.f, 0.f, 0.f, 0.f};
;                 ag[n] = g4s * al; ab[n] = b4s * al; }
;             f32x4 xa[3][2]; f2_t_ ms[3];
;     ...
;             RES_LOADG(0, 0); RES_LOADG(1, 1);
	v_cndmask_b32_e64 v127, v142, 0, s[28:29]
	v_lshl_add_u64 v[92:93], v[172:173], 0, s[38:39]
	s_mov_b32 s38, 0x160000
	v_add_co_u32_e32 v106, vcc, s38, v172
	v_cndmask_b32_e64 v126, v143, 1.0, s[28:29]
	s_nop 0
	v_addc_co_u32_e32 v107, vcc, 0, v173, vcc
	global_load_dwordx4 v[96:99], v[106:107], off
	s_nop 0
	global_load_dwordx4 v[92:95], v[92:93], off offset:16
	s_nop 0
	global_load_dwordx2 v[124:125], v[170:171], off offset:1408
	v_pk_mul_f32 v[128:129], v[188:189], v[126:127] op_sel_hi:[1,0]
	v_pk_mul_f32 v[130:131], v[186:187], v[126:127] op_sel_hi:[1,0]
	v_sub_f32_e32 v113, v113, v127
	v_sub_f32_e32 v112, v112, v127
	v_sub_f32_e32 v115, v115, v127
	v_sub_f32_e32 v114, v114, v127
	v_pk_fma_f32 v[90:91], v[130:131], v[114:115], v[90:91]
	v_pk_fma_f32 v[88:89], v[128:129], v[112:113], v[88:89]
	global_store_dwordx4 v[140:141], v[88:91], off
	v_sub_f32_e32 v109, v109, v127
	v_sub_f32_e32 v108, v108, v127
	v_pk_mul_f32 v[88:89], v[184:185], v[126:127] op_sel_hi:[1,0]
	v_pk_mul_f32 v[90:91], v[190:191], v[126:127] op_sel_hi:[1,0]
	v_sub_f32_e32 v111, v111, v127
	v_sub_f32_e32 v110, v110, v127
	v_pk_fma_f32 v[86:87], v[90:91], v[110:111], v[86:87]
	v_pk_fma_f32 v[84:85], v[88:89], v[108:109], v[84:85]
	global_store_dwordx4 v[140:141], v[84:87], off offset:16
	v_cndmask_b32_e64 v110, v136, 0, s[28:29]
	v_sub_f32_e32 v91, v133, v110
	v_cndmask_b32_e64 v84, v137, 1.0, s[28:29]
	v_pk_mul_f32 v[86:87], v[188:189], v[84:85] op_sel_hi:[1,0]
	v_pk_mul_f32 v[88:89], v[186:187], v[84:85] op_sel_hi:[1,0]
	v_sub_f32_e32 v90, v132, v110
	v_sub_f32_e32 v109, v135, v110
	v_sub_f32_e32 v108, v134, v110
	v_pk_fma_f32 v[82:83], v[88:89], v[108:109], v[82:83]
	v_pk_fma_f32 v[80:81], v[86:87], v[90:91], v[80:81]
	global_store_dwordx4 v[104:105], v[80:83], off
	v_sub_f32_e32 v87, v103, v110
	v_sub_f32_e32 v86, v102, v110
	v_pk_mul_f32 v[80:81], v[184:185], v[84:85] op_sel_hi:[1,0]
	v_pk_mul_f32 v[82:83], v[190:191], v[84:85] op_sel_hi:[1,0]
	v_sub_f32_e32 v85, v101, v110
	v_sub_f32_e32 v84, v100, v110
	v_pk_fma_f32 v[78:79], v[82:83], v[86:87], v[78:79]
	v_pk_fma_f32 v[76:77], v[80:81], v[84:85], v[76:77]
	global_store_dwordx4 v[104:105], v[76:79], off offset:16
	s_and_b64 vcc, exec, s[4:5]
	v_mov_b32_e32 v87, 0x3fb504f3
	s_waitcnt vmcnt(0)
	v_cndmask_b32_e64 v86, v124, 0, s[28:29]
	v_cndmask_b32_e64 v76, v125, 1.0, s[28:29]
	v_pk_mul_f32 v[78:79], v[188:189], v[76:77] op_sel_hi:[1,0]
	v_pk_mul_f32 v[80:81], v[186:187], v[76:77] op_sel_hi:[1,0]
	v_sub_f32_e32 v83, v97, v86
	v_sub_f32_e32 v82, v96, v86
	v_sub_f32_e32 v85, v99, v86
	v_sub_f32_e32 v84, v98, v86
	v_pk_fma_f32 v[74:75], v[80:81], v[84:85], v[74:75]
	v_pk_fma_f32 v[72:73], v[78:79], v[82:83], v[72:73]
	global_store_dwordx4 v[106:107], v[72:75], off
	v_sub_f32_e32 v79, v95, v86
	v_sub_f32_e32 v78, v94, v86
	v_pk_mul_f32 v[72:73], v[184:185], v[76:77] op_sel_hi:[1,0]
	v_pk_mul_f32 v[74:75], v[190:191], v[76:77] op_sel_hi:[1,0]
	v_sub_f32_e32 v77, v93, v86
	v_sub_f32_e32 v76, v92, v86
	v_pk_fma_f32 v[70:71], v[74:75], v[78:79], v[70:71]
	v_pk_fma_f32 v[68:69], v[72:73], v[76:77], v[68:69]
	global_store_dwordx4 v[106:107], v[68:71], off offset:16
	global_load_dwordx4 v[68:71], v[182:183], off offset:512
	global_load_dwordx4 v[80:83], v[178:179], off offset:512
	v_mov_b32_e32 v84, 0x3fb504f3
	v_mov_b32_e32 v85, 0x3fb504f3
	v_mov_b32_e32 v86, 0x3fb504f3
	global_load_dwordx4 v[72:75], v[182:183], off offset:528
	global_load_dwordx4 v[76:79], v[178:179], off offset:528
	s_cbranch_vccnz .LBB0_1082
	global_load_dwordx4 v[244:247], v[180:181], off offset:512
	global_load_dwordx4 v[92:95], v[180:181], off offset:528
	s_waitcnt vmcnt(0)
	v_pk_mul_f32 v[86:87], v[246:247], s[40:41] op_sel_hi:[1,0]
	v_pk_mul_f32 v[84:85], v[244:245], s[40:41] op_sel_hi:[1,0]
	v_pk_mul_f32 v[90:91], v[82:83], s[40:41] op_sel_hi:[1,0]
	v_pk_mul_f32 v[88:89], v[80:81], s[40:41] op_sel_hi:[1,0]
	v_pk_mul_f32 v[82:83], v[94:95], s[40:41] op_sel_hi:[1,0]
	v_pk_mul_f32 v[80:81], v[92:93], s[40:41] op_sel_hi:[1,0]
	s_branch .LBB0_1083
.LBB0_1080:
.LBB0_1082:
	s_waitcnt vmcnt(0)
	v_mov_b32_e32 v80, 0x3fb504f3
	v_mov_b32_e32 v88, 0
	v_mov_b32_e32 v89, v88
	v_mov_b32_e32 v90, v88
	v_mov_b32_e32 v91, v88
	v_mov_b32_e32 v81, v80
	v_mov_b32_e32 v82, v80
	v_mov_b32_e32 v83, v80

; #define RES_LOADG(slot, g_) do { const int ro_ = ((g_) >> 2) * HALF + ((g_) & 3) * 16; \
;                 _Pragma("unroll") for (int n = 0; n < 2; ++n) xa[slot][n] = *(const f32x4*)(sl + rbase + (size_t)ro_ * 2048 + bj * HALF + 4 * n); \
;                 ms[slot] = *(const f2_t_*)(stp + 2 * (row0 + ro_)); } while (0)
;     __device__ __forceinline__ void operator()(const f32x4 (&acc)[2][2][4][2], const Unit& u, int wr, int wc, int fr, int fq) const {
;     ...
; #pragma unroll
;         for (int bj = 0; bj < 2; ++bj) {
;             f32x4 mv[2], ag[2], ab[2];
; #pragma unroll
;             for (int n = 0; n < 2; ++n) { mv[n] = *(const f32x4*)(mp + col0 + bj * HALF + 4 * n) * coef;
;                 const f32x4 g4 = *(const f32x4*)(lg + col0 + bj * HALF + 4 * n), b4 = *(const f32x4*)(lb + col0 + bj * HALF + 4 * n);
;                 const f32x4 g4s = ln ? g4 : (f32x4){1.f, 1.f, 1.f, 1.f}, b4s = ln ? b4 : (f32x4){0.f, 0.f, 0.f, 0.f};
;                 ag[n] = g4s * al; ab[n] = b4s * al; }
;             f32x4 xa[3][2]; f2_t_ ms[3];
;     ...
;             RES_LOADG(0, 0); RES_LOADG(1, 1);
.LBB0_1335:
	s_ashr_i32 s4, s71, 3
	s_mul_hi_i32 s5, s4, 0x12000
	s_mul_i32 s4, s4, 0x12000
	v_lshl_or_b32 v148, s73, 8, v218
	s_add_u32 s4, s54, s4
	v_ashrrev_i32_e32 v149, 31, v148
	s_addc_u32 s5, s55, s5
	v_lshlrev_b64 v[138:139], 2, v[148:149]
	v_lshl_add_u64 v[136:137], s[4:5], 0, v[138:139]
	v_add_co_u32_e32 v132, vcc, 0x10000, v136
	v_lshl_add_u64 v[170:171], s[20:21], 0, v[138:139]
	s_nop 0
	v_addc_co_u32_e32 v133, vcc, 0, v137, vcc
	global_load_dwordx4 v[132:135], v[132:133], off
	s_nop 0
	global_load_dwordx4 v[140:143], v[170:171], off
	v_lshl_add_u64 v[172:173], s[6:7], 0, v[138:139]
	v_cndmask_b32_e64 v138, 0, 1, s[26:27]
	v_mov_b32_e32 v176, 0x3fb504f3
	v_cmp_ne_u32_e64 s[4:5], 1, v138
	s_andn2_b64 vcc, exec, s[26:27]
	v_mov_b32_e32 v180, 0x3fb504f3
	v_mov_b32_e32 v181, 0x3fb504f3
	v_mov_b32_e32 v178, 0x3fb504f3
	v_mov_b32_e32 v179, 0x3fb504f3
	s_mov_b64 s[38:39], 0x10000
	v_lshl_add_u64 v[174:175], v[136:137], 0, s[38:39]
	global_load_dwordx4 v[144:147], v[174:175], off offset:16
	global_load_dwordx4 v[136:139], v[170:171], off offset:16
	v_mov_b32_e32 v177, 0x3fb504f3
	v_mov_b32_e32 v182, 0x3fb504f3
	v_mov_b32_e32 v183, 0x3fb504f3
	s_cbranch_vccnz .LBB0_1339
	global_load_dwordx4 v[244:247], v[172:173], off
	global_load_dwordx4 v[162:165], v[172:173], off offset:16
	s_waitcnt vmcnt(0)
	v_pk_mul_f32 v[178:179], v[246:247], s[40:41] op_sel_hi:[1,0]
	v_pk_mul_f32 v[180:181], v[244:245], s[40:41] op_sel_hi:[1,0]
	v_pk_mul_f32 v[182:183], v[164:165], s[40:41] op_sel_hi:[1,0]
	v_pk_mul_f32 v[176:177], v[162:163], s[40:41] op_sel_hi:[1,0]
.LBB0_1337:
.LBB0_1339:
	s_waitcnt vmcnt(0)
	v_pk_mul_f32 v[140:141], v[140:141], s[40:41] op_sel_hi:[1,0]
	v_pk_mul_f32 v[208:209], v[132:133], 0.5 op_sel_hi:[1,0]
	v_cndmask_b32_e64 v188, v140, 0, s[28:29]
	v_lshl_add_u32 v140, s71, 8, v216
	v_cndmask_b32_e64 v189, v141, 0, s[28:29]
	v_ashrrev_i32_e32 v141, 31, v140
	v_pk_mul_f32 v[132:133], v[138:139], s[40:41] op_sel_hi:[1,0]
	s_mov_b64 s[38:39], 0x20000
	v_cndmask_b32_e64 v207, v133, 0, s[28:29]
	v_cndmask_b32_e64 v206, v132, 0, s[28:29]
	v_lshlrev_b64 v[132:133], 13, v[140:141]
	v_lshl_add_u64 v[132:133], s[8:9], 0, v[132:133]
	v_lshl_add_u64 v[164:165], v[148:149], 2, v[132:133]
	v_pk_mul_f32 v[142:143], v[142:143], s[40:41] op_sel_hi:[1,0]
	v_lshl_add_u64 v[132:133], v[164:165], 0, s[38:39]
	s_mov_b32 s38, 0x20000
	v_cndmask_b32_e64 v190, v142, 0, s[28:29]
	v_lshlrev_b32_e32 v142, 1, v140
	v_add_co_u32_e32 v168, vcc, s38, v164
	v_cndmask_b32_e64 v191, v143, 0, s[28:29]
	v_ashrrev_i32_e32 v143, 31, v142
	v_addc_co_u32_e32 v169, vcc, 0, v165, vcc
	v_pk_mul_f32 v[186:187], v[146:147], 0.5 op_sel_hi:[1,0]
	v_pk_mul_f32 v[184:185], v[144:145], 0.5 op_sel_hi:[1,0]
	v_lshl_add_u64 v[162:163], v[142:143], 2, s[30:31]
	global_load_dwordx4 v[148:151], v[164:165], off offset:16
	global_load_dwordx4 v[220:223], v[164:165], off
	global_load_dwordx4 v[144:147], v[168:169], off
	global_load_dwordx4 v[140:143], v[132:133], off offset:16
	global_load_dwordx2 v[192:193], v[162:163], off
	global_load_dwordx2 v[214:215], v[162:163], off offset:128
	s_mov_b64 s[38:39], 0x40000
	v_pk_mul_f32 v[210:211], v[134:135], 0.5 op_sel_hi:[1,0]
	v_lshl_add_u64 v[132:133], v[164:165], 0, s[38:39]
	s_mov_b32 s38, 0x40000
	v_pk_mul_f32 v[134:135], v[136:137], s[40:41] op_sel_hi:[1,0]
	v_add_co_u32_e32 v166, vcc, s38, v164
	v_pk_fma_f32 v[130:131], v[130:131], v[210:211], v[190:191]
	v_pk_fma_f32 v[128:129], v[128:129], v[208:209], v[188:189]
	v_cndmask_b32_e64 v205, v135, 0, s[28:29]
	v_cndmask_b32_e64 v204, v134, 0, s[28:29]
	v_addc_co_u32_e32 v167, vcc, 0, v165, vcc
	global_load_dwordx4 v[136:139], v[166:167], off
	s_nop 0
	global_load_dwordx4 v[132:135], v[132:133], off offset:16
	s_nop 0
	global_load_dwordx2 v[212:213], v[162:163], off offset:256
	v_pk_fma_f32 v[126:127], v[126:127], v[186:187], v[206:207]
	v_pk_fma_f32 v[124:125], v[124:125], v[184:185], v[204:205]
	s_mov_b64 s[38:39], 0x60000
	v_pk_fma_f32 v[122:123], v[122:123], v[210:211], v[190:191]
	v_pk_fma_f32 v[120:121], v[120:121], v[208:209], v[188:189]
	v_pk_fma_f32 v[118:119], v[118:119], v[186:187], v[206:207]
	v_pk_fma_f32 v[116:117], v[116:117], v[184:185], v[204:205]
	v_pk_fma_f32 v[114:115], v[114:115], v[210:211], v[190:191]
	v_pk_fma_f32 v[112:113], v[112:113], v[208:209], v[188:189]
	v_pk_fma_f32 v[110:111], v[110:111], v[186:187], v[206:207]
	v_pk_fma_f32 v[108:109], v[108:109], v[184:185], v[204:205]
	v_pk_fma_f32 v[106:107], v[106:107], v[210:211], v[190:191]
	v_pk_fma_f32 v[104:105], v[104:105], v[208:209], v[188:189]
	v_pk_fma_f32 v[102:103], v[102:103], v[186:187], v[206:207]
	v_pk_fma_f32 v[100:101], v[100:101], v[184:185], v[204:205]
	v_pk_fma_f32 v[98:99], v[98:99], v[210:211], v[190:191]
	v_pk_fma_f32 v[96:97], v[96:97], v[208:209], v[188:189]
	v_pk_fma_f32 v[94:95], v[94:95], v[186:187], v[206:207]
	v_pk_fma_f32 v[92:93], v[92:93], v[184:185], v[204:205]
	v_pk_fma_f32 v[90:91], v[90:91], v[210:211], v[190:191]
	v_pk_fma_f32 v[88:89], v[88:89], v[208:209], v[188:189]
	v_pk_fma_f32 v[86:87], v[86:87], v[186:187], v[206:207]
	v_pk_fma_f32 v[84:85], v[84:85], v[184:185], v[204:205]
	v_pk_fma_f32 v[82:83], v[82:83], v[210:211], v[190:191]
	v_pk_fma_f32 v[80:81], v[80:81], v[208:209], v[188:189]
	v_pk_fma_f32 v[78:79], v[78:79], v[186:187], v[206:207]
	v_pk_fma_f32 v[76:77], v[76:77], v[184:185], v[204:205]
	v_pk_fma_f32 v[74:75], v[74:75], v[210:211], v[190:191]
	v_pk_fma_f32 v[72:73], v[72:73], v[208:209], v[188:189]
	v_pk_fma_f32 v[70:71], v[70:71], v[186:187], v[206:207]
	v_pk_fma_f32 v[68:69], v[68:69], v[184:185], v[204:205]
	s_waitcnt vmcnt(0)
; #define RES_LOADG(slot, g_) do { const int ro_ = ((g_) >> 2) * HALF + ((g_) & 3) * 16; \
;                 _Pragma("unroll") for (int n = 0; n < 2; ++n) xa[slot][n] = *(const f32x4*)(sl + rbase + (size_t)ro_ * 2048 + bj * HALF + 4 * n); \
;                 ms[slot] = *(const f2_t_*)(stp + 2 * (row0 + ro_)); } while (0)
;     __device__ __forceinline__ void operator()(const f32x4 (&acc)[2][2][4][2], const Unit& u, int wr, int wc, int fr, int fq) const {
;     ...
; #pragma unroll
;             for (int gi = 0; gi < 8; ++gi) {
;                 const int ai = gi >> 2, m = gi & 3;
;                 if (gi + 2 < 8) RES_LOADG((gi + 2) % 3, gi + 2);
;                 asm volatile("" ::: "memory");
;                 float* rowp = xl + rbase + (size_t)(ai * HALF + m * 16) * 2048 + bj * HALF;
;                 const float mean = ln ? ms[gi % 3][0] : 0.f, rstd = ln ? ms[gi % 3][1] : 1.f;
; #pragma unroll
;                 for (int n = 0; n < 2; ++n) { const f32x4 t = ag[n] * rstd;
;                     *(f32x4*)(rowp + 4 * n) = (xa[gi % 3][n] - mean) * t + (ab[n] + mv[n] * acc[ai][bj][m][n]); }
;                 asm volatile("" ::: "memory");
;             }
	v_cndmask_b32_e64 v228, v192, 0, s[28:29]
	v_cndmask_b32_e64 v192, v193, 1.0, s[28:29]
	v_pk_mul_f32 v[196:197], v[180:181], v[192:193] op_sel_hi:[1,0]
	v_pk_mul_f32 v[198:199], v[178:179], v[192:193] op_sel_hi:[1,0]
	v_sub_f32_e32 v201, v221, v228
	v_sub_f32_e32 v200, v220, v228
	v_sub_f32_e32 v203, v223, v228
	v_sub_f32_e32 v202, v222, v228
	v_pk_fma_f32 v[130:131], v[198:199], v[202:203], v[130:131]
	v_pk_fma_f32 v[128:129], v[196:197], v[200:201], v[128:129]
	global_store_dwordx4 v[164:165], v[128:131], off
	v_sub_f32_e32 v149, v149, v228
	v_sub_f32_e32 v148, v148, v228
	v_pk_mul_f32 v[128:129], v[176:177], v[192:193] op_sel_hi:[1,0]
	v_pk_mul_f32 v[130:131], v[182:183], v[192:193] op_sel_hi:[1,0]
	v_sub_f32_e32 v151, v151, v228
	v_sub_f32_e32 v150, v150, v228
	v_pk_fma_f32 v[126:127], v[130:131], v[150:151], v[126:127]
	v_pk_fma_f32 v[124:125], v[128:129], v[148:149], v[124:125]
	global_store_dwordx4 v[164:165], v[124:127], off offset:16
	v_cndmask_b32_e64 v193, v214, 0, s[28:29]
	v_cndmask_b32_e64 v192, v215, 1.0, s[28:29]
	v_lshl_add_u64 v[124:125], v[164:165], 0, s[38:39]
	s_mov_b32 s38, 0x60000
	v_add_co_u32_e32 v148, vcc, s38, v164
	v_pk_mul_f32 v[196:197], v[180:181], v[192:193] op_sel_hi:[1,0]
	v_pk_mul_f32 v[198:199], v[178:179], v[192:193] op_sel_hi:[1,0]
	v_sub_f32_e32 v145, v145, v193
	v_sub_f32_e32 v144, v144, v193
	v_sub_f32_e32 v147, v147, v193
	v_sub_f32_e32 v146, v146, v193
	v_addc_co_u32_e32 v149, vcc, 0, v165, vcc
	v_pk_fma_f32 v[122:123], v[198:199], v[146:147], v[122:123]
	v_pk_fma_f32 v[120:121], v[196:197], v[144:145], v[120:121]
	global_load_dwordx4 v[128:131], v[148:149], off
	s_nop 0
	global_load_dwordx4 v[124:127], v[124:125], off offset:16
	s_nop 0
	global_load_dwordx2 v[150:151], v[162:163], off offset:384
	global_store_dwordx4 v[168:169], v[120:123], off
	v_pk_mul_f32 v[144:145], v[182:183], v[192:193] op_sel_hi:[1,0]
	s_mov_b64 s[38:39], 0x100000
	v_pk_mul_f32 v[120:121], v[176:177], v[192:193] op_sel_hi:[1,0]
	v_sub_f32_e32 v123, v141, v193
	v_sub_f32_e32 v122, v140, v193
	v_sub_f32_e32 v141, v143, v193
	v_sub_f32_e32 v140, v142, v193
	v_pk_fma_f32 v[118:119], v[144:145], v[140:141], v[118:119]
	v_pk_fma_f32 v[116:117], v[120:121], v[122:123], v[116:117]
	global_store_dwordx4 v[168:169], v[116:119], off offset:16
	v_cndmask_b32_e64 v145, v212, 0, s[28:29]
	v_cndmask_b32_e64 v144, v213, 1.0, s[28:29]
	v_lshl_add_u64 v[116:117], v[164:165], 0, s[38:39]
	s_mov_b32 s38, 0x100000
	v_add_co_u32_e32 v140, vcc, s38, v164
	v_pk_mul_f32 v[146:147], v[180:181], v[144:145] op_sel_hi:[1,0]
	s_nop 0
	v_addc_co_u32_e32 v141, vcc, 0, v165, vcc
	global_load_dwordx4 v[120:123], v[140:141], off
	s_nop 0
	global_load_dwordx4 v[116:119], v[116:117], off offset:16
	s_nop 0
	global_load_dwordx2 v[142:143], v[162:163], off offset:1024
	v_pk_mul_f32 v[192:193], v[178:179], v[144:145] op_sel_hi:[1,0]
	v_sub_f32_e32 v137, v137, v145
	v_sub_f32_e32 v136, v136, v145
	v_sub_f32_e32 v139, v139, v145
	v_sub_f32_e32 v138, v138, v145
	v_pk_fma_f32 v[114:115], v[192:193], v[138:139], v[114:115]
	v_pk_fma_f32 v[112:113], v[146:147], v[136:137], v[112:113]
	global_store_dwordx4 v[166:167], v[112:115], off
	v_sub_f32_e32 v133, v133, v145
	v_sub_f32_e32 v132, v132, v145
	v_pk_mul_f32 v[112:113], v[176:177], v[144:145] op_sel_hi:[1,0]
	v_pk_mul_f32 v[114:115], v[182:183], v[144:145] op_sel_hi:[1,0]
	v_sub_f32_e32 v135, v135, v145
	v_sub_f32_e32 v134, v134, v145
	v_pk_fma_f32 v[110:111], v[114:115], v[134:135], v[110:111]
	v_pk_fma_f32 v[108:109], v[112:113], v[132:133], v[108:109]
	s_mov_b64 s[38:39], 0x120000
	global_store_dwordx4 v[166:167], v[108:111], off offset:16
	s_waitcnt vmcnt(0)
	v_cndmask_b32_e64 v137, v150, 0, s[28:29]
	v_lshl_add_u64 v[108:109], v[164:165], 0, s[38:39]
	s_mov_b32 s38, 0x120000
	v_cndmask_b32_e64 v136, v151, 1.0, s[28:29]
	v_add_co_u32_e32 v132, vcc, s38, v164
	v_pk_mul_f32 v[138:139], v[180:181], v[136:137] op_sel_hi:[1,0]
	v_pk_mul_f32 v[144:145], v[178:179], v[136:137] op_sel_hi:[1,0]
	v_sub_f32_e32 v129, v129, v137
	v_sub_f32_e32 v128, v128, v137
	v_sub_f32_e32 v131, v131, v137
	v_sub_f32_e32 v130, v130, v137
	v_addc_co_u32_e32 v133, vcc, 0, v165, vcc
	v_pk_fma_f32 v[106:107], v[144:145], v[130:131], v[106:107]
	v_pk_fma_f32 v[104:105], v[138:139], v[128:129], v[104:105]
	global_load_dwordx4 v[112:115], v[132:133], off
	s_nop 0
	global_load_dwordx4 v[108:111], v[108:109], off offset:16
	s_nop 0
	global_load_dwordx2 v[134:135], v[162:163], off offset:1152
	global_store_dwordx4 v[148:149], v[104:107], off
	v_sub_f32_e32 v125, v125, v137
	v_sub_f32_e32 v124, v124, v137
	v_pk_mul_f32 v[104:105], v[176:177], v[136:137] op_sel_hi:[1,0]
	v_pk_mul_f32 v[106:107], v[182:183], v[136:137] op_sel_hi:[1,0]
	v_sub_f32_e32 v127, v127, v137
	v_sub_f32_e32 v126, v126, v137
	v_pk_fma_f32 v[102:103], v[106:107], v[126:127], v[102:103]
	v_pk_fma_f32 v[100:101], v[104:105], v[124:125], v[100:101]
	s_mov_b64 s[38:39], 0x140000
	global_store_dwordx4 v[148:149], v[100:103], off offset:16
	v_cndmask_b32_e64 v138, v142, 0, s[28:29]
	v_cndmask_b32_e64 v106, v143, 1.0, s[28:29]
	v_lshl_add_u64 v[100:101], v[164:165], 0, s[38:39]
	s_mov_b32 s38, 0x140000
	v_add_co_u32_e32 v104, vcc, s38, v164
	v_pk_mul_f32 v[130:131], v[180:181], v[106:107] op_sel_hi:[1,0]
	v_pk_mul_f32 v[136:137], v[178:179], v[106:107] op_sel_hi:[1,0]
	v_sub_f32_e32 v121, v121, v138
	v_sub_f32_e32 v120, v120, v138
	v_sub_f32_e32 v123, v123, v138
	v_sub_f32_e32 v122, v122, v138
	v_addc_co_u32_e32 v105, vcc, 0, v165, vcc
	v_pk_fma_f32 v[98:99], v[136:137], v[122:123], v[98:99]
	v_pk_fma_f32 v[96:97], v[130:131], v[120:121], v[96:97]
	global_load_dwordx4 v[124:127], v[104:105], off
	s_nop 0
	global_load_dwordx4 v[100:103], v[100:101], off offset:16
	s_nop 0
	global_load_dwordx2 v[128:129], v[162:163], off offset:1280
	global_store_dwordx4 v[140:141], v[96:99], off
	s_mov_b64 s[38:39], 0x160000
	s_nop 0
	v_pk_mul_f32 v[96:97], v[176:177], v[106:107] op_sel_hi:[1,0]
	v_pk_mul_f32 v[98:99], v[182:183], v[106:107] op_sel_hi:[1,0]
	v_sub_f32_e32 v107, v117, v138
	v_sub_f32_e32 v106, v116, v138
	v_sub_f32_e32 v117, v119, v138
	v_sub_f32_e32 v116, v118, v138
	v_pk_fma_f32 v[94:95], v[98:99], v[116:117], v[94:95]
	v_pk_fma_f32 v[92:93], v[96:97], v[106:107], v[92:93]
	global_store_dwordx4 v[140:141], v[92:95], off offset:16
	s_waitcnt vmcnt(0)
; #define RES_LOADG(slot, g_) do { const int ro_ = ((g_) >> 2) * HALF + ((g_) & 3) * 16; \
;                 _Pragma("unroll") for (int n = 0; n < 2; ++n) xa[slot][n] = *(const f32x4*)(sl + rbase + (size_t)ro_ * 2048 + bj * HALF + 4 * n); \
;                 ms[slot] = *(const f2_t_*)(stp + 2 * (row0 + ro_)); } while (0)
;     __device__ __forceinline__ void operator()(const f32x4 (&acc)[2][2][4][2], const Unit& u, int wr, int wc, int fr, int fq) const {
;     ...
; #pragma unroll
;         for (int bj = 0; bj < 2; ++bj) {
;             f32x4 mv[2], ag[2], ab[2];
; #pragma unroll
;             for (int n = 0; n < 2; ++n) { mv[n] = *(const f32x4*)(mp + col0 + bj * HALF + 4 * n) * coef;
;                 const f32x4 g4 = *(const f32x4*)(lg + col0 + bj * HALF + 4 * n), b4 = *(const f32x4*)(lb + col0 + bj * HALF + 4 * n);
;                 const f32x4 g4s = ln ? g4 : (f32x4){1.f, 1.f, 1.f, 1.f}, b4s = ln ? b4 : (f32x4){0.f, 0.f, 0.f, 0.f};
;                 ag[n] = g4s * al; ab[n] = b4s * al; }
;             f32x4 xa[3][2]; f2_t_ ms[3];
;     ...
;             RES_LOADG(0, 0); RES_LOADG(1, 1);
	v_cndmask_b32_e64 v119, v134, 0, s[28:29]
	v_lshl_add_u64 v[92:93], v[164:165], 0, s[38:39]
	s_mov_b32 s38, 0x160000
	v_add_co_u32_e32 v106, vcc, s38, v164
	v_cndmask_b32_e64 v118, v135, 1.0, s[28:29]
	s_nop 0
	v_addc_co_u32_e32 v107, vcc, 0, v165, vcc
	global_load_dwordx4 v[96:99], v[106:107], off
	s_nop 0
	global_load_dwordx4 v[92:95], v[92:93], off offset:16
	s_nop 0
	global_load_dwordx2 v[116:117], v[162:163], off offset:1408
	v_pk_mul_f32 v[120:121], v[180:181], v[118:119] op_sel_hi:[1,0]
	v_pk_mul_f32 v[122:123], v[178:179], v[118:119] op_sel_hi:[1,0]
	v_sub_f32_e32 v113, v113, v119
	v_sub_f32_e32 v112, v112, v119
	v_sub_f32_e32 v115, v115, v119
	v_sub_f32_e32 v114, v114, v119
	v_pk_fma_f32 v[90:91], v[122:123], v[114:115], v[90:91]
	v_pk_fma_f32 v[88:89], v[120:121], v[112:113], v[88:89]
	global_store_dwordx4 v[132:133], v[88:91], off
	v_sub_f32_e32 v109, v109, v119
	v_sub_f32_e32 v108, v108, v119
	v_pk_mul_f32 v[88:89], v[176:177], v[118:119] op_sel_hi:[1,0]
	v_pk_mul_f32 v[90:91], v[182:183], v[118:119] op_sel_hi:[1,0]
	v_sub_f32_e32 v111, v111, v119
	v_sub_f32_e32 v110, v110, v119
	v_pk_fma_f32 v[86:87], v[90:91], v[110:111], v[86:87]
	v_pk_fma_f32 v[84:85], v[88:89], v[108:109], v[84:85]
	global_store_dwordx4 v[132:133], v[84:87], off offset:16
	v_cndmask_b32_e64 v110, v128, 0, s[28:29]
	v_sub_f32_e32 v91, v125, v110
	v_cndmask_b32_e64 v84, v129, 1.0, s[28:29]
	v_pk_mul_f32 v[86:87], v[180:181], v[84:85] op_sel_hi:[1,0]
	v_pk_mul_f32 v[88:89], v[178:179], v[84:85] op_sel_hi:[1,0]
	v_sub_f32_e32 v90, v124, v110
	v_sub_f32_e32 v109, v127, v110
	v_sub_f32_e32 v108, v126, v110
	v_pk_fma_f32 v[82:83], v[88:89], v[108:109], v[82:83]
	v_pk_fma_f32 v[80:81], v[86:87], v[90:91], v[80:81]
	global_store_dwordx4 v[104:105], v[80:83], off
	v_sub_f32_e32 v87, v103, v110
	v_sub_f32_e32 v86, v102, v110
	v_pk_mul_f32 v[80:81], v[176:177], v[84:85] op_sel_hi:[1,0]
	v_pk_mul_f32 v[82:83], v[182:183], v[84:85] op_sel_hi:[1,0]
	v_sub_f32_e32 v85, v101, v110
	v_sub_f32_e32 v84, v100, v110
	v_pk_fma_f32 v[78:79], v[82:83], v[86:87], v[78:79]
	v_pk_fma_f32 v[76:77], v[80:81], v[84:85], v[76:77]
	global_store_dwordx4 v[104:105], v[76:79], off offset:16
	s_and_b64 vcc, exec, s[4:5]
	v_mov_b32_e32 v87, 0x3fb504f3
	s_waitcnt vmcnt(0)
	v_cndmask_b32_e64 v86, v116, 0, s[28:29]
	v_cndmask_b32_e64 v76, v117, 1.0, s[28:29]
	v_pk_mul_f32 v[78:79], v[180:181], v[76:77] op_sel_hi:[1,0]
	v_pk_mul_f32 v[80:81], v[178:179], v[76:77] op_sel_hi:[1,0]
	v_sub_f32_e32 v83, v97, v86
	v_sub_f32_e32 v82, v96, v86
	v_sub_f32_e32 v85, v99, v86
	v_sub_f32_e32 v84, v98, v86
	v_pk_fma_f32 v[74:75], v[80:81], v[84:85], v[74:75]
	v_pk_fma_f32 v[72:73], v[78:79], v[82:83], v[72:73]
	global_store_dwordx4 v[106:107], v[72:75], off
	v_sub_f32_e32 v79, v95, v86
	v_sub_f32_e32 v78, v94, v86
	v_pk_mul_f32 v[72:73], v[176:177], v[76:77] op_sel_hi:[1,0]
	v_pk_mul_f32 v[74:75], v[182:183], v[76:77] op_sel_hi:[1,0]
	v_sub_f32_e32 v77, v93, v86
	v_sub_f32_e32 v76, v92, v86
	v_pk_fma_f32 v[70:71], v[74:75], v[78:79], v[70:71]
	v_pk_fma_f32 v[68:69], v[72:73], v[76:77], v[68:69]
	global_store_dwordx4 v[106:107], v[68:71], off offset:16
	global_load_dwordx4 v[68:71], v[174:175], off offset:512
	global_load_dwordx4 v[80:83], v[170:171], off offset:512
	v_mov_b32_e32 v84, 0x3fb504f3
	v_mov_b32_e32 v85, 0x3fb504f3
	v_mov_b32_e32 v86, 0x3fb504f3
	global_load_dwordx4 v[76:79], v[174:175], off offset:528
	global_load_dwordx4 v[72:75], v[170:171], off offset:528
	s_cbranch_vccnz .LBB0_1343
	global_load_dwordx4 v[244:247], v[172:173], off offset:512
	global_load_dwordx4 v[92:95], v[172:173], off offset:528
	s_waitcnt vmcnt(0)
	v_pk_mul_f32 v[86:87], v[246:247], s[40:41] op_sel_hi:[1,0]
	v_pk_mul_f32 v[84:85], v[244:245], s[40:41] op_sel_hi:[1,0]
	v_pk_mul_f32 v[90:91], v[82:83], s[40:41] op_sel_hi:[1,0]
	v_pk_mul_f32 v[88:89], v[80:81], s[40:41] op_sel_hi:[1,0]
	v_pk_mul_f32 v[82:83], v[94:95], s[40:41] op_sel_hi:[1,0]
	v_pk_mul_f32 v[80:81], v[92:93], s[40:41] op_sel_hi:[1,0]
	s_branch .LBB0_1344
